# stack on the reads-before-init version: early first PV0 MFMA, Q fragment prefetch before the tile barrier, straightened common path, GEMM segment head trimmed
# baseline (speedup 1.0000x reference)
; #define LAS __attribute__((address_space(3)))
; #define AT_RAISE(MP) do { if (trig[MP]) { const float dl = fmaxf(__builtin_amdgcn_logf(pmx[MP]), 0.f), al = __builtin_amdgcn_exp2f(-dl); mref[MP] += dl; lsum[MP] *= al; \
;                 _Pragma("unroll") for (int cb = 0; cb < 4; ++cb) o[MP][cb] = o[MP][cb] * al; } } while (0)
; __device__ __forceinline__ void dattn_unit(LAS unsigned char* lds, int b, int h, int qb, const bf16* Q, const bf16* K, const bf16* V, bf16* YB, float lam, const float* subg, float oml, int tid) {
;     ...
;                 bf16x8 ka = *(const LAS bf16x8*)kp, kb = *(const LAS bf16x8*)(kp + 64 * 72), qa = qsp[0], qb = qsp[4 * 64];
;                 __builtin_amdgcn_sched_group_barrier(0x100, 4, 0);
; #pragma unroll
;                 for (int ks = 0; ks < 4; ++ks) { bf16x8 ka2 = ka, kb2 = kb, qa2 = qa, qb2 = qb;
;                     if (ks < 3) { ka2 = *(const LAS bf16x8*)(kp + (ks + 1) * 16); kb2 = *(const LAS bf16x8*)(kp + 64 * 72 + (ks + 1) * 16); qa2 = qsp[(ks + 1) * 64]; qb2 = qsp[(4 + ks + 1) * 64];
;     ...
;             for (int cb = 0; cb < 4; ++cb) { const LAS bf16* vp = Vt + (32 * cb + ql) * 72 + 32 * sub + 4 * hi;
;                 const v2u a0 = *(const LAS v2u*)(vp), a1 = *(const LAS v2u*)(vp + 8), a2 = *(const LAS v2u*)(vp + 16), a3 = *(const LAS v2u*)(vp + 24);
;                 const v4u f0 = {a0.x, a0.y, a1.x, a1.y}, f1 = {a2.x, a2.y, a3.x, a3.y};
;                 o[0][cb] = __builtin_amdgcn_mfma_f32_32x32x16_bf16(__builtin_bit_cast(bf16x8, f0), pA0, o[0][cb], 0, 0, 0);
;                 o[1][cb] = __builtin_amdgcn_mfma_f32_32x32x16_bf16(__builtin_bit_cast(bf16x8, f0), pA1, o[1][cb], 0, 0, 0);
;                 o[0][cb] = __builtin_amdgcn_mfma_f32_32x32x16_bf16(__builtin_bit_cast(bf16x8, f1), pB0, o[0][cb], 0, 0, 0);
;                 o[1][cb] = __builtin_amdgcn_mfma_f32_32x32x16_bf16(__builtin_bit_cast(bf16x8, f1), pB1, o[1][cb], 0, 0, 0); }
;             AT_RAISE(0); AT_RAISE(1);
;         }
;     ...
;         }
;         if (t + 1 < NT) AT_STAGE((t + 1) & 1);
;         __syncthreads();
.LBB0_245:
	v_cvt_pk_bf16_f32 v152, v155, v129
	v_cvt_pk_bf16_f32 v153, v130, v131
	v_cvt_pk_bf16_f32 v154, v132, v156
	v_cvt_pk_bf16_f32 v155, v157, v158
	v_cvt_pk_bf16_f32 v130, v133, v134
	v_cvt_pk_bf16_f32 v131, v135, v136
	v_cvt_pk_bf16_f32 v132, v137, v138
	v_cvt_pk_bf16_f32 v133, v139, v140
	s_xor_b32 s18, s38, 0x9000
	v_add3_u32 v148, s18, v196, v180
	v_add3_u32 v149, s18, v197, v195
	s_andn2_b64 vcc, exec, s[48:49]
	s_nop 0
	v_mfma_f32_32x32x16_bf16 v[64:79], v[222:225], v[152:155], v[64:79]
	s_waitcnt vmcnt(3)
	ds_write_b128 v148, v[168:171]
	ds_read_b128 v[204:207], v189
	v_mfma_f32_32x32x16_bf16 v[64:79], v[226:229], v[130:133], v[64:79]
	s_waitcnt vmcnt(2)
	ds_write_b128 v148, v[172:175] offset:9216
	v_mfma_f32_32x32x16_bf16 v[32:47], v[230:233], v[152:155], v[32:47]
	ds_read_b128 v[230:233], v189 offset:1024
	s_waitcnt vmcnt(1)
	ds_write_b16 v149, v164 offset:18432
	ds_write_b16_d16_hi v149, v164 offset:18576
	ds_write_b16 v149, v165 offset:18720
	v_mfma_f32_32x32x16_bf16 v[32:47], v[234:237], v[130:133], v[32:47]
	ds_read_b128 v[234:237], v189 offset:5120
	ds_write_b16_d16_hi v149, v165 offset:18864
	ds_write_b16 v149, v166 offset:19008
	ds_write_b16_d16_hi v149, v166 offset:19152
	v_mfma_f32_32x32x16_bf16 v[96:111], v[212:215], v[152:155], v[96:111]
	ds_write_b16 v149, v167 offset:19296
	ds_write_b16_d16_hi v149, v167 offset:19440
	s_waitcnt vmcnt(0)
	ds_write_b16 v149, v160 offset:19584
	v_mfma_f32_32x32x16_bf16 v[96:111], v[200:203], v[130:133], v[96:111]
	ds_write_b16_d16_hi v149, v160 offset:19728
	ds_write_b16 v149, v161 offset:19872
	ds_write_b16_d16_hi v149, v161 offset:20016
	v_mfma_f32_32x32x16_bf16 v[0:15], v[238:241], v[152:155], v[0:15]
	ds_write_b16 v149, v162 offset:20160
	ds_write_b16_d16_hi v149, v162 offset:20304
	v_mfma_f32_32x32x16_bf16 v[0:15], v[218:221], v[130:133], v[0:15]
	ds_read_b128 v[218:221], v189 offset:4096
	ds_write_b16 v149, v163 offset:20448
	ds_write_b16_d16_hi v149, v163 offset:20592
	s_or_b64 vcc, s[48:49], s[46:47]
	s_cbranch_vccnz .Lrare_s1
	v_add_f32_e32 v181, v181, v128
	s_add_i32 s59, s59, 1
	s_bitcmp1_b32 s59, 0
	s_cselect_b32 s18, 0x9000, 0
	s_add_i32 s60, s18, 0
	s_addk_i32 s57, 0x100
	s_add_i32 s58, s58, 64
	s_add_u32 s98, s98, s14
	s_addc_u32 s99, s99, s15
	s_add_u32 s100, s100, s14
	s_addc_u32 s101, s101, s15
	s_cmp_lg_u32 s56, s57
	s_waitcnt lgkmcnt(0)
	s_barrier
	s_cbranch_scc1 .LBB0_227
